# static priority raise (s_setprio 1) for the heavier wave of each SIMD pair (lt=2,3 paths) in the ssd_scan chunk loop, lowered again before the loop-back
# speedup vs baseline: 1.0031x; 1.0031x over previous
; __device__ __forceinline__ void ssd_scan_mfma(const Ctx& c, bf16* X2, const float* DT, const float* a_log, const float* dskip, bool do_store) {
;     ...
;                 const float csl = CS[16 * lt + l15];
;                 bf16x8 Cf[4];
; #pragma unroll
;                 for (int ks = 0; ks < 4; ++ks) Cf[ks] = *(const LAS bf16x8*)(L + SS_C + (16 * lt + l15) * 272 + (32 * ks + 8 * lg) * 2);
;                 f32x4 GT[4];
; #pragma unroll
;                 for (int st = 0; st < 4; ++st) { GT[st] = (f32x4){0.f, 0.f, 0.f, 0.f};
;                     if (st <= lt) {
; #pragma unroll
;                         for (int ks = 0; ks < 4; ++ks) { const bf16x8 bf = *(const LAS bf16x8*)(L + SS_B + (16 * st + l15) * 272 + (32 * ks + 8 * lg) * 2); GT[st] = __builtin_amdgcn_mfma_f32_16x16x32_bf16(bf, Cf[ks], GT[st], 0, 0, 0); }
;                         const f32x4 css = *(const LAS f32x4*)(CS + 16 * st + 4 * lg);
; #pragma unroll
;                         for (int r = 0; r < 4; ++r) { const bool ok = (16 * st + 4 * lg + r) <= (16 * lt + l15); GT[st][r] = ok ? GT[st][r] * __expf(csl - css[r]) : 0.f; }
;                     } }
;                 bf16x8 Lf[2];
; #pragma unroll
;                 for (int k2 = 0; k2 < 2; ++k2) { v4u q; q.x = pg8::cvt_pk_bf16(GT[2 * k2][0], GT[2 * k2][1]); q.y = pg8::cvt_pk_bf16(GT[2 * k2][2], GT[2 * k2][3]); q.z = pg8::cvt_pk_bf16(GT[2 * k2 + 1][0], GT[2 * k2 + 1][1]); q.w = pg8::cvt_pk_bf16(GT[2 * k2 + 1][2], GT[2 * k2 + 1][3]);
;                     Lf[k2] = __builtin_bit_cast(bf16x8, q); }
;                 const float el = __expf(csl);
;                 const LAS unsigned char* xdb = L + SS_XD + (4 * lg + tq) * 144 + tp * 8;
; #pragma unroll
;                 for (int pp = 0; pp < 2; ++pp) { const int pt = 2 * ph + pp; f32x4 Y = (f32x4){0.f, 0.f, 0.f, 0.f}, Yo = (f32x4){0.f, 0.f, 0.f, 0.f};
; #pragma unroll
;                     for (int k2 = 0; k2 < 2; ++k2) if (2 * k2 <= lt) { const LAS unsigned char* xp = xdb + k2 * 32 * 144 + pt * 32;
;                         Y = __builtin_amdgcn_mfma_f32_16x16x32_bf16(cat8(tr16(xp), tr16(xp + 16 * 144)), Lf[k2], Y, 0, 0, 0); }
; #pragma unroll
;                     for (int ks = 0; ks < 4; ++ks) { const bf16x8 sb = *(const LAS bf16x8*)(SBr + (16 * pt + l15) * 272 + (32 * ks + 8 * lg) * 2); Yo = __builtin_amdgcn_mfma_f32_16x16x32_bf16(sb, Cf[ks], Yo, 0, 0, 0); }
.Lmy_scan_lt3:
	s_setprio 1
	ds_read_b32 v106, v69
	ds_read_b128 v[42:45], v139 offset:17408
	ds_read_b128 v[46:49], v139 offset:17472
	ds_read_b128 v[50:53], v139 offset:17536
	ds_read_b128 v[56:59], v139 offset:17600
	ds_read_b128 v[166:169], v133 offset:13056
	ds_read_b128 v[170:173], v133 offset:13120
	ds_read_b128 v[174:177], v133 offset:13184
	ds_read_b128 v[178:181], v133 offset:13248
	ds_read_b128 v[182:185], v141 offset:192
	s_mulk_i32 s96, 0x4400
	s_mulk_i32 s76, 0x4400
	s_add_u32 s10, s4, 0x23400000
	s_addc_u32 s11, s5, 0
	ds_read_b128 v[186:189], v133 offset:8704
	ds_read_b128 v[190:193], v133 offset:8768
	ds_read_b128 v[194:197], v133 offset:8832
	ds_read_b128 v[198:201], v133 offset:8896
	ds_read_b128 v[202:205], v141 offset:128
	v_add3_u32 v69, s96, v115, v120
	v_add3_u32 v107, s96, v115, v121
	v_add_u32_e32 v55, s76, v125
	s_waitcnt lgkmcnt(9)
	v_mfma_f32_16x16x32_bf16 v[166:169], v[166:169], v[42:45], 0
	s_waitcnt lgkmcnt(8)
	v_mfma_f32_16x16x32_bf16 v[166:169], v[170:173], v[46:49], v[166:169]
	s_waitcnt lgkmcnt(7)
	v_mfma_f32_16x16x32_bf16 v[166:169], v[174:177], v[50:53], v[166:169]
	s_waitcnt lgkmcnt(6)
	v_mfma_f32_16x16x32_bf16 v[166:169], v[178:181], v[56:59], v[166:169]
	ds_read_b128 v[206:209], v133 offset:4352
	ds_read_b128 v[210:213], v133 offset:4416
	ds_read_b128 v[214:217], v133 offset:4480
	ds_read_b128 v[218:221], v133 offset:4544
	ds_read_b128 v[222:225], v141 offset:64
	s_waitcnt lgkmcnt(9)
	v_mfma_f32_16x16x32_bf16 v[186:189], v[186:189], v[42:45], 0
	s_waitcnt lgkmcnt(8)
	v_mfma_f32_16x16x32_bf16 v[186:189], v[190:193], v[46:49], v[186:189]
	s_waitcnt lgkmcnt(7)
	v_mfma_f32_16x16x32_bf16 v[186:189], v[194:197], v[50:53], v[186:189]
	s_waitcnt lgkmcnt(6)
	v_mfma_f32_16x16x32_bf16 v[186:189], v[198:201], v[56:59], v[186:189]
	ds_read_b128 v[226:229], v133
	ds_read_b128 v[230:233], v133 offset:64
	ds_read_b128 v[234:237], v133 offset:128
	ds_read_b128 v[238:241], v133 offset:192
	ds_read_b128 v[242:245], v141
	v_sub_f32_e32 v182, v106, v182
	v_sub_f32_e32 v183, v106, v183
	v_sub_f32_e32 v184, v106, v184
	v_sub_f32_e32 v185, v106, v185
	v_mul_f32_e32 v182, 0x3fb8aa3b, v182
	v_mul_f32_e32 v183, 0x3fb8aa3b, v183
	v_mul_f32_e32 v184, 0x3fb8aa3b, v184
	v_mul_f32_e32 v185, 0x3fb8aa3b, v185
	v_exp_f32_e32 v182, v182
	v_exp_f32_e32 v183, v183
	v_exp_f32_e32 v184, v184
	v_exp_f32_e32 v185, v185
	v_mul_f32_e32 v166, v166, v182
	v_mul_f32_e32 v167, v167, v183
	v_mul_f32_e32 v168, v168, v184
	v_mul_f32_e32 v169, v169, v185
	v_cndmask_b32_e64 v166, v166, 0, s[42:43]
	v_cndmask_b32_e64 v167, v167, 0, s[44:45]
	v_cndmask_b32_e64 v168, v168, 0, s[46:47]
	v_cndmask_b32_e64 v169, v169, 0, s[48:49]
	s_waitcnt lgkmcnt(9)
	v_mfma_f32_16x16x32_bf16 v[206:209], v[206:209], v[42:45], 0
	s_waitcnt lgkmcnt(8)
	v_mfma_f32_16x16x32_bf16 v[206:209], v[210:213], v[46:49], v[206:209]
	s_waitcnt lgkmcnt(7)
	v_mfma_f32_16x16x32_bf16 v[206:209], v[214:217], v[50:53], v[206:209]
	s_waitcnt lgkmcnt(6)
	v_mfma_f32_16x16x32_bf16 v[206:209], v[218:221], v[56:59], v[206:209]
	ds_read_b64_tr_b16 v[60:61], v140 offset:44032
	ds_read_b64_tr_b16 v[62:63], v140 offset:46336
	ds_read_b64_tr_b16 v[64:65], v140 offset:48640
	ds_read_b64_tr_b16 v[66:67], v140 offset:50944
	v_sub_f32_e32 v202, v106, v202
	v_sub_f32_e32 v203, v106, v203
	v_sub_f32_e32 v204, v106, v204
	v_sub_f32_e32 v205, v106, v205
	v_mul_f32_e32 v202, 0x3fb8aa3b, v202
	v_mul_f32_e32 v203, 0x3fb8aa3b, v203
	v_mul_f32_e32 v204, 0x3fb8aa3b, v204
	v_mul_f32_e32 v205, 0x3fb8aa3b, v205
	v_exp_f32_e32 v202, v202
	v_exp_f32_e32 v203, v203
	v_exp_f32_e32 v204, v204
	v_exp_f32_e32 v205, v205
	v_mul_f32_e32 v186, v186, v202
	v_mul_f32_e32 v187, v187, v203
	v_mul_f32_e32 v188, v188, v204
	v_mul_f32_e32 v189, v189, v205
	v_cndmask_b32_e64 v186, v186, 0, s[34:35]
	v_cndmask_b32_e64 v187, v187, 0, s[36:37]
	v_cndmask_b32_e64 v188, v188, 0, s[38:39]
	v_cndmask_b32_e64 v189, v189, 0, s[40:41]
	s_waitcnt lgkmcnt(8)
	v_mfma_f32_16x16x32_bf16 v[226:229], v[226:229], v[42:45], 0
	s_waitcnt lgkmcnt(7)
	v_mfma_f32_16x16x32_bf16 v[226:229], v[230:233], v[46:49], v[226:229]
	s_waitcnt lgkmcnt(6)
	v_mfma_f32_16x16x32_bf16 v[226:229], v[234:237], v[50:53], v[226:229]
	s_waitcnt lgkmcnt(5)
	v_mfma_f32_16x16x32_bf16 v[226:229], v[238:241], v[56:59], v[226:229]
	ds_read_b64_tr_b16 v[142:143], v68 offset:44032
	ds_read_b64_tr_b16 v[144:145], v68 offset:46336
	ds_read_b64_tr_b16 v[146:147], v68 offset:48640
	ds_read_b64_tr_b16 v[148:149], v68 offset:50944
	v_sub_f32_e32 v222, v106, v222
	v_sub_f32_e32 v223, v106, v223
	v_sub_f32_e32 v224, v106, v224
	v_sub_f32_e32 v225, v106, v225
	v_mul_f32_e32 v222, 0x3fb8aa3b, v222
	v_mul_f32_e32 v223, 0x3fb8aa3b, v223
	v_mul_f32_e32 v224, 0x3fb8aa3b, v224
	v_mul_f32_e32 v225, 0x3fb8aa3b, v225
	v_exp_f32_e32 v222, v222
	v_exp_f32_e32 v223, v223
	v_exp_f32_e32 v224, v224
	v_exp_f32_e32 v225, v225
	v_mul_f32_e32 v206, v206, v222
	v_mul_f32_e32 v207, v207, v223
	v_mul_f32_e32 v208, v208, v224
	v_mul_f32_e32 v209, v209, v225
	v_cndmask_b32_e64 v206, v206, 0, s[24:25]
	v_cndmask_b32_e64 v207, v207, 0, s[26:27]
	v_cndmask_b32_e64 v208, v208, 0, s[28:29]
	v_cndmask_b32_e64 v209, v209, 0, s[30:31]
	ds_read_b128 v[150:153], v69 offset:62464
	ds_read_b128 v[154:157], v69 offset:62528
	ds_read_b128 v[158:161], v69 offset:62592
	ds_read_b128 v[246:249], v69 offset:62656
	ds_read_b64 v[162:163], v134 offset:34816
	s_waitcnt lgkmcnt(4)
	v_mfma_f32_16x16x32_bf16 v[150:153], v[150:153], v[42:45], 0
	s_waitcnt lgkmcnt(3)
	v_mfma_f32_16x16x32_bf16 v[150:153], v[154:157], v[46:49], v[150:153]
	s_waitcnt lgkmcnt(2)
	v_mfma_f32_16x16x32_bf16 v[150:153], v[158:161], v[50:53], v[150:153]
	s_waitcnt lgkmcnt(1)
; #define LAS __attribute__((address_space(3)))
; __device__ __forceinline__ unsigned pk2(float lo, float hi) { return f2bf(lo) | (f2bf(hi) << 16); }
; __device__ __forceinline__ void ssd_scan_mfma(const Ctx& c, bf16* X2, const float* DT, const float* a_log, const float* dskip, bool do_store) {
;     ...
;                     for (int k2 = 0; k2 < 2; ++k2) if (2 * k2 <= lt) { const LAS unsigned char* xp = xdb + k2 * 32 * 144 + pt * 32;
;                         Y = __builtin_amdgcn_mfma_f32_16x16x32_bf16(cat8(tr16(xp), tr16(xp + 16 * 144)), Lf[k2], Y, 0, 0, 0); }
; #pragma unroll
;                     for (int ks = 0; ks < 4; ++ks) { const bf16x8 sb = *(const LAS bf16x8*)(SBr + (16 * pt + l15) * 272 + (32 * ks + 8 * lg) * 2); Yo = __builtin_amdgcn_mfma_f32_16x16x32_bf16(sb, Cf[ks], Yo, 0, 0, 0); }
;                     const v2u xr = *(const LAS v2u*)(L + SS_XR + (16 * lt + l15) * 144 + (16 * pt + 4 * lg) * 2);
;                     const float y0 = Y[0] + el * Yo[0] + Dh * bflo(xr.x), y1 = Y[1] + el * Yo[1] + Dh * bfhi(xr.x), y2 = Y[2] + el * Yo[2] + Dh * bflo(xr.y), y3 = Y[3] + el * Yo[3] + Dh * bfhi(xr.y);
;                     v2u o; o.x = pk2(y0, y1); o.y = pk2(y2, y3);
;                     if (do_store) *(v2u*)(X2 + ((size_t)b * SEQ + t0 + 16 * lt + l15) * 6144 + h * 64 + 16 * pt + 4 * lg) = o; }
;                 const float e63 = __expf(CS[63]); const int pts = w >> 1;
;                 const LAS unsigned char* bb = L + SS_B + (8 * lg + tq) * 272 + tp * 8; const LAS unsigned char* xwb = L + SS_XW + (8 * lg + tq) * 144 + tp * 8 + pts * 32;
;                 bf16x8 Xf[2];
; #pragma unroll
;                 for (int ks = 0; ks < 2; ++ks) Xf[ks] = cat8(tr16(xwb + ks * 32 * 144), tr16(xwb + ks * 32 * 144 + 4 * 144));
; #pragma unroll
;                 for (int i = 0; i < 4; ++i) { const int nt = 4 * (w & 1) + i; ST[i] *= e63;
; #pragma unroll
;                     for (int ks = 0; ks < 2; ++ks) { const LAS unsigned char* bp = bb + ks * 32 * 272 + nt * 32;
;                         ST[i] = __builtin_amdgcn_mfma_f32_16x16x32_bf16(cat8(tr16(bp), tr16(bp + 4 * 272)), Xf[ks], ST[i], 0, 0, 0); }
;                     v2u q; q.x = pk2(ST[i][0], ST[i][1]); q.y = pk2(ST[i][2], ST[i][3]);
;                     *(LAS v2u*)(SBw + (16 * pts + l15) * 272 + (16 * nt + 4 * lg) * 2) = q; }
	v_mfma_f32_16x16x32_bf16 v[150:153], v[246:249], v[56:59], v[150:153]
	v_sub_f32_e32 v242, v106, v242
	v_sub_f32_e32 v243, v106, v243
	v_sub_f32_e32 v244, v106, v244
	v_sub_f32_e32 v245, v106, v245
	v_mul_f32_e32 v242, 0x3fb8aa3b, v242
	v_mul_f32_e32 v243, 0x3fb8aa3b, v243
	v_mul_f32_e32 v244, 0x3fb8aa3b, v244
	v_mul_f32_e32 v245, 0x3fb8aa3b, v245
	v_exp_f32_e32 v242, v242
	v_exp_f32_e32 v243, v243
	v_exp_f32_e32 v244, v244
	v_exp_f32_e32 v245, v245
	v_mul_f32_e32 v226, v226, v242
	v_mul_f32_e32 v227, v227, v243
	v_mul_f32_e32 v228, v228, v244
	v_mul_f32_e32 v229, v229, v245
	v_cndmask_b32_e64 v226, v226, 0, s[16:17]
	v_cndmask_b32_e64 v227, 0, v227, s[18:19]
	v_cndmask_b32_e64 v228, v228, 0, s[20:21]
	v_cndmask_b32_e64 v229, v229, 0, s[22:23]
	v_mul_f32_e32 v106, 0x3fb8aa3b, v106
	v_exp_f32_e32 v106, v106
	v_cvt_pk_bf16_f32 v226, v226, v227
	v_cvt_pk_bf16_f32 v227, v228, v229
	v_cvt_pk_bf16_f32 v228, v206, v207
	v_cvt_pk_bf16_f32 v229, v208, v209
	v_cvt_pk_bf16_f32 v186, v186, v187
	v_cvt_pk_bf16_f32 v187, v188, v189
	v_cvt_pk_bf16_f32 v188, v166, v167
	v_cvt_pk_bf16_f32 v189, v168, v169
	v_mov_b32_e32 v168, s65
	ds_read_b128 v[170:173], v107 offset:62464
	ds_read_b128 v[174:177], v107 offset:62528
	ds_read_b128 v[178:181], v107 offset:62592
	ds_read_b128 v[182:185], v107 offset:62656
	ds_read_b64 v[166:167], v136 offset:34816
	ds_read_b32 v168, v168 offset:252
	v_lshl_add_u64 v[238:239], s[10:11], 0, v[98:99]
	v_mfma_f32_16x16x32_bf16 v[60:63], v[60:63], v[226:229], 0
	v_mfma_f32_16x16x32_bf16 v[60:63], v[64:67], v[186:189], v[60:63]
	v_mfma_f32_16x16x32_bf16 v[142:145], v[142:145], v[226:229], 0
	v_mfma_f32_16x16x32_bf16 v[142:145], v[146:149], v[186:189], v[142:145]
	s_waitcnt lgkmcnt(5)
	v_mfma_f32_16x16x32_bf16 v[170:173], v[170:173], v[42:45], 0
	s_waitcnt lgkmcnt(4)
	v_mfma_f32_16x16x32_bf16 v[170:173], v[174:177], v[46:49], v[170:173]
	s_waitcnt lgkmcnt(3)
	v_mfma_f32_16x16x32_bf16 v[170:173], v[178:181], v[50:53], v[170:173]
	s_waitcnt lgkmcnt(2)
	v_mfma_f32_16x16x32_bf16 v[170:173], v[182:185], v[56:59], v[170:173]
	ds_read_b64_tr_b16 v[190:191], v137 offset:53248
	ds_read_b64_tr_b16 v[192:193], v137 offset:53824
	ds_read_b64_tr_b16 v[194:195], v137 offset:57856
	ds_read_b64_tr_b16 v[196:197], v137 offset:58432
	ds_read_b64_tr_b16 v[198:199], v54
	ds_read_b64_tr_b16 v[200:201], v54 offset:1088
	ds_read_b64_tr_b16 v[202:203], v54 offset:8704
	ds_read_b64_tr_b16 v[204:205], v54 offset:9792
	s_waitcnt lgkmcnt(8)
	v_mul_f32_e32 v168, 0x3fb8aa3b, v168
	v_exp_f32_e32 v168, v168
	v_fma_f32 v60, v106, v150, v60
	v_fma_f32 v61, v106, v151, v61
	v_fma_f32 v62, v106, v152, v62
	v_fma_f32 v63, v106, v153, v63
	v_lshlrev_b32_e32 v150, 16, v162
	v_and_b32_e32 v151, 0xffff0000, v162
	v_lshlrev_b32_e32 v152, 16, v163
	v_and_b32_e32 v153, 0xffff0000, v163
	v_fma_f32 v60, v94, v150, v60
	v_fma_f32 v61, v94, v151, v61
	v_fma_f32 v62, v95, v152, v62
	v_fma_f32 v63, v95, v153, v63
	v_cvt_pk_bf16_f32 v162, v60, v61
	v_cvt_pk_bf16_f32 v163, v62, v63
	global_store_dwordx2 v[238:239], v[162:163], off
	v_pk_mul_f32 v[18:19], v[18:19], v[168:169] op_sel_hi:[1,0]
	v_pk_mul_f32 v[20:21], v[20:21], v[168:169] op_sel_hi:[1,0]
	v_pk_mul_f32 v[14:15], v[14:15], v[168:169] op_sel_hi:[1,0]
	v_pk_mul_f32 v[16:17], v[16:17], v[168:169] op_sel_hi:[1,0]
	v_pk_mul_f32 v[10:11], v[10:11], v[168:169] op_sel_hi:[1,0]
	v_pk_mul_f32 v[12:13], v[12:13], v[168:169] op_sel_hi:[1,0]
	v_pk_mul_f32 v[6:7], v[6:7], v[168:169] op_sel_hi:[1,0]
	v_pk_mul_f32 v[8:9], v[8:9], v[168:169] op_sel_hi:[1,0]
	s_waitcnt lgkmcnt(2)
	v_mfma_f32_16x16x32_bf16 v[18:21], v[198:201], v[190:193], v[18:21]
	s_waitcnt lgkmcnt(0)
	v_mfma_f32_16x16x32_bf16 v[18:21], v[202:205], v[194:197], v[18:21]
	ds_read_b64_tr_b16 v[210:211], v54 offset:32
	ds_read_b64_tr_b16 v[212:213], v54 offset:1120
	ds_read_b64_tr_b16 v[214:215], v54 offset:8736
	ds_read_b64_tr_b16 v[216:217], v54 offset:9824
	v_fma_f32 v142, v106, v170, v142
	v_fma_f32 v143, v106, v171, v143
	v_fma_f32 v144, v106, v172, v144
	v_fma_f32 v145, v106, v173, v145
	v_lshlrev_b32_e32 v170, 16, v166
	v_and_b32_e32 v171, 0xffff0000, v166
	v_lshlrev_b32_e32 v172, 16, v167
	v_and_b32_e32 v173, 0xffff0000, v167
	v_fma_f32 v142, v94, v170, v142
	v_fma_f32 v143, v94, v171, v143
	v_fma_f32 v144, v95, v172, v144
	v_fma_f32 v145, v95, v173, v145
	v_cvt_pk_bf16_f32 v166, v142, v143
	v_cvt_pk_bf16_f32 v167, v144, v145
	global_store_dwordx2 v[238:239], v[166:167], off offset:32
	s_waitcnt lgkmcnt(2)
	v_mfma_f32_16x16x32_bf16 v[14:17], v[210:213], v[190:193], v[14:17]
	s_waitcnt lgkmcnt(0)
	v_mfma_f32_16x16x32_bf16 v[14:17], v[214:217], v[194:197], v[14:17]
	ds_read_b64_tr_b16 v[218:219], v54 offset:64
	ds_read_b64_tr_b16 v[220:221], v54 offset:1152
	ds_read_b64_tr_b16 v[222:223], v54 offset:8768
	ds_read_b64_tr_b16 v[224:225], v54 offset:9856
	v_cvt_pk_bf16_f32 v240, v18, v19
	v_cvt_pk_bf16_f32 v241, v20, v21
	ds_write_b64 v55, v[240:241] offset:62464
	s_waitcnt lgkmcnt(3)
	v_mfma_f32_16x16x32_bf16 v[10:13], v[218:221], v[190:193], v[10:13]
	s_waitcnt lgkmcnt(1)
	v_mfma_f32_16x16x32_bf16 v[10:13], v[222:225], v[194:197], v[10:13]
	ds_read_b64_tr_b16 v[230:231], v54 offset:96
	ds_read_b64_tr_b16 v[232:233], v54 offset:1184
	ds_read_b64_tr_b16 v[234:235], v54 offset:8800
	ds_read_b64_tr_b16 v[236:237], v54 offset:9888
	v_cvt_pk_bf16_f32 v242, v14, v15
	v_cvt_pk_bf16_f32 v243, v16, v17
	ds_write_b64 v55, v[242:243] offset:62496
	s_waitcnt lgkmcnt(3)
	v_mfma_f32_16x16x32_bf16 v[6:9], v[230:233], v[190:193], v[6:9]
	s_waitcnt lgkmcnt(1)
	v_mfma_f32_16x16x32_bf16 v[6:9], v[234:237], v[194:197], v[6:9]
	s_mov_b64 s[96:97], 0x4000
	s_add_i32 s63, s63, 1
	v_lshl_add_u64 v[96:97], v[96:97], 0, s[96:97]
	v_lshl_add_u64 v[98:99], v[98:99], 0, s[58:59]
	v_lshl_add_u64 v[100:101], v[100:101], 0, s[58:59]
	v_lshl_add_u64 v[102:103], v[102:103], 0, s[58:59]
	v_lshl_add_u64 v[104:105], v[104:105], 0, s[58:59]
	v_cvt_pk_bf16_f32 v240, v10, v11
	v_cvt_pk_bf16_f32 v241, v12, v13
	ds_write_b64 v55, v[240:241] offset:62528
	s_cmp_eq_u32 s63, 63
	v_cvt_pk_bf16_f32 v242, v6, v7
	v_cvt_pk_bf16_f32 v243, v8, v9
	ds_write_b64 v55, v[242:243] offset:62560
	s_setprio 0
	s_cbranch_scc1 .LBB0_483
	s_branch .LBB0_469
; #define LAS __attribute__((address_space(3)))
; __device__ __forceinline__ unsigned cvt_pk_bf16(float lo, float hi) { unsigned r; asm volatile("v_cvt_pk_bf16_f32 %0, %1, %2" : "=v"(r) : "v"(lo), "v"(hi)); return r; }
; __device__ __forceinline__ void ssd_scan_mfma(const Ctx& c, bf16* X2, const float* DT, const float* a_log, const float* dskip, bool do_store) {
;     ...
;                 const float csl = CS[16 * lt + l15];
;                 bf16x8 Cf[4];
; #pragma unroll
;                 for (int ks = 0; ks < 4; ++ks) Cf[ks] = *(const LAS bf16x8*)(L + SS_C + (16 * lt + l15) * 272 + (32 * ks + 8 * lg) * 2);
;                 f32x4 GT[4];
; #pragma unroll
;                 for (int st = 0; st < 4; ++st) { GT[st] = (f32x4){0.f, 0.f, 0.f, 0.f};
;                     if (st <= lt) {
; #pragma unroll
;                         for (int ks = 0; ks < 4; ++ks) { const bf16x8 bf = *(const LAS bf16x8*)(L + SS_B + (16 * st + l15) * 272 + (32 * ks + 8 * lg) * 2); GT[st] = __builtin_amdgcn_mfma_f32_16x16x32_bf16(bf, Cf[ks], GT[st], 0, 0, 0); }
;                         const f32x4 css = *(const LAS f32x4*)(CS + 16 * st + 4 * lg);
; #pragma unroll
;                         for (int r = 0; r < 4; ++r) { const bool ok = (16 * st + 4 * lg + r) <= (16 * lt + l15); GT[st][r] = ok ? GT[st][r] * __expf(csl - css[r]) : 0.f; }
;                     } }
;                 bf16x8 Lf[2];
; #pragma unroll
;                 for (int k2 = 0; k2 < 2; ++k2) { v4u q; q.x = pg8::cvt_pk_bf16(GT[2 * k2][0], GT[2 * k2][1]); q.y = pg8::cvt_pk_bf16(GT[2 * k2][2], GT[2 * k2][3]); q.z = pg8::cvt_pk_bf16(GT[2 * k2 + 1][0], GT[2 * k2 + 1][1]); q.w = pg8::cvt_pk_bf16(GT[2 * k2 + 1][2], GT[2 * k2 + 1][3]);
;                     Lf[k2] = __builtin_bit_cast(bf16x8, q); }
;                 const float el = __expf(csl);
;                 const LAS unsigned char* xdb = L + SS_XD + (4 * lg + tq) * 144 + tp * 8;
; #pragma unroll
;                 for (int pp = 0; pp < 2; ++pp) { const int pt = 2 * ph + pp; f32x4 Y = (f32x4){0.f, 0.f, 0.f, 0.f}, Yo = (f32x4){0.f, 0.f, 0.f, 0.f};
; #pragma unroll
;                     for (int k2 = 0; k2 < 2; ++k2) if (2 * k2 <= lt) { const LAS unsigned char* xp = xdb + k2 * 32 * 144 + pt * 32;
;                         Y = __builtin_amdgcn_mfma_f32_16x16x32_bf16(cat8(tr16(xp), tr16(xp + 16 * 144)), Lf[k2], Y, 0, 0, 0); }
.Lmy_scan_lt2:
	s_setprio 1
	ds_read_b32 v106, v69
	ds_read_b128 v[42:45], v139 offset:17408
	ds_read_b128 v[46:49], v139 offset:17472
	ds_read_b128 v[50:53], v139 offset:17536
	ds_read_b128 v[56:59], v139 offset:17600
	ds_read_b128 v[186:189], v133 offset:8704
	ds_read_b128 v[190:193], v133 offset:8768
	ds_read_b128 v[194:197], v133 offset:8832
	ds_read_b128 v[198:201], v133 offset:8896
	ds_read_b128 v[202:205], v141 offset:128
	s_mulk_i32 s96, 0x4400
	s_mulk_i32 s76, 0x4400
	s_add_u32 s10, s4, 0x23400000
	s_addc_u32 s11, s5, 0
	ds_read_b128 v[206:209], v133 offset:4352
	ds_read_b128 v[210:213], v133 offset:4416
	ds_read_b128 v[214:217], v133 offset:4480
	ds_read_b128 v[218:221], v133 offset:4544
	ds_read_b128 v[222:225], v141 offset:64
	v_add3_u32 v69, s96, v115, v120
	v_add3_u32 v107, s96, v115, v121
	v_add_u32_e32 v55, s76, v125
	s_waitcnt lgkmcnt(9)
	v_mfma_f32_16x16x32_bf16 v[186:189], v[186:189], v[42:45], 0
	s_waitcnt lgkmcnt(8)
	v_mfma_f32_16x16x32_bf16 v[186:189], v[190:193], v[46:49], v[186:189]
	s_waitcnt lgkmcnt(7)
	v_mfma_f32_16x16x32_bf16 v[186:189], v[194:197], v[50:53], v[186:189]
	s_waitcnt lgkmcnt(6)
	v_mfma_f32_16x16x32_bf16 v[186:189], v[198:201], v[56:59], v[186:189]
	ds_read_b128 v[226:229], v133
	ds_read_b128 v[230:233], v133 offset:64
	ds_read_b128 v[234:237], v133 offset:128
	ds_read_b128 v[238:241], v133 offset:192
	ds_read_b128 v[242:245], v141
	s_waitcnt lgkmcnt(9)
	v_mfma_f32_16x16x32_bf16 v[206:209], v[206:209], v[42:45], 0
	s_waitcnt lgkmcnt(8)
	v_mfma_f32_16x16x32_bf16 v[206:209], v[210:213], v[46:49], v[206:209]
	s_waitcnt lgkmcnt(7)
	v_mfma_f32_16x16x32_bf16 v[206:209], v[214:217], v[50:53], v[206:209]
	s_waitcnt lgkmcnt(6)
	v_mfma_f32_16x16x32_bf16 v[206:209], v[218:221], v[56:59], v[206:209]
	ds_read_b64_tr_b16 v[60:61], v140 offset:44032
	ds_read_b64_tr_b16 v[62:63], v140 offset:46336
	ds_read_b64_tr_b16 v[64:65], v140 offset:48640
	ds_read_b64_tr_b16 v[66:67], v140 offset:50944
	v_sub_f32_e32 v202, v106, v202
	v_sub_f32_e32 v203, v106, v203
	v_sub_f32_e32 v204, v106, v204
	v_sub_f32_e32 v205, v106, v205
	v_mul_f32_e32 v202, 0x3fb8aa3b, v202
	v_mul_f32_e32 v203, 0x3fb8aa3b, v203
	v_mul_f32_e32 v204, 0x3fb8aa3b, v204
	v_mul_f32_e32 v205, 0x3fb8aa3b, v205
	v_exp_f32_e32 v202, v202
	v_exp_f32_e32 v203, v203
	v_exp_f32_e32 v204, v204
	v_exp_f32_e32 v205, v205
	v_mul_f32_e32 v186, v186, v202
	v_mul_f32_e32 v187, v187, v203
	v_mul_f32_e32 v188, v188, v204
	v_mul_f32_e32 v189, v189, v205
	v_cndmask_b32_e64 v186, v186, 0, s[34:35]
	v_cndmask_b32_e64 v187, v187, 0, s[36:37]
	v_cndmask_b32_e64 v188, v188, 0, s[38:39]
	v_cndmask_b32_e64 v189, v189, 0, s[40:41]
	s_waitcnt lgkmcnt(8)
	v_mfma_f32_16x16x32_bf16 v[226:229], v[226:229], v[42:45], 0
	s_waitcnt lgkmcnt(7)
	v_mfma_f32_16x16x32_bf16 v[226:229], v[230:233], v[46:49], v[226:229]
	s_waitcnt lgkmcnt(6)
	v_mfma_f32_16x16x32_bf16 v[226:229], v[234:237], v[50:53], v[226:229]
	s_waitcnt lgkmcnt(5)
	v_mfma_f32_16x16x32_bf16 v[226:229], v[238:241], v[56:59], v[226:229]
	ds_read_b64_tr_b16 v[142:143], v68 offset:44032
	ds_read_b64_tr_b16 v[144:145], v68 offset:46336
	ds_read_b64_tr_b16 v[146:147], v68 offset:48640
	ds_read_b64_tr_b16 v[148:149], v68 offset:50944
	v_sub_f32_e32 v222, v106, v222
	v_sub_f32_e32 v223, v106, v223
	v_sub_f32_e32 v224, v106, v224
	v_sub_f32_e32 v225, v106, v225
	v_mul_f32_e32 v222, 0x3fb8aa3b, v222
	v_mul_f32_e32 v223, 0x3fb8aa3b, v223
	v_mul_f32_e32 v224, 0x3fb8aa3b, v224
	v_mul_f32_e32 v225, 0x3fb8aa3b, v225
	v_exp_f32_e32 v222, v222
	v_exp_f32_e32 v223, v223
	v_exp_f32_e32 v224, v224
	v_exp_f32_e32 v225, v225
	v_mul_f32_e32 v206, v206, v222
	v_mul_f32_e32 v207, v207, v223
	v_mul_f32_e32 v208, v208, v224
	v_mul_f32_e32 v209, v209, v225
	v_cndmask_b32_e64 v206, v206, 0, s[24:25]
	v_cndmask_b32_e64 v207, v207, 0, s[26:27]
	v_cndmask_b32_e64 v208, v208, 0, s[28:29]
	v_cndmask_b32_e64 v209, v209, 0, s[30:31]
	ds_read_b128 v[150:153], v69 offset:62464
	ds_read_b128 v[154:157], v69 offset:62528
	ds_read_b128 v[158:161], v69 offset:62592
	ds_read_b128 v[246:249], v69 offset:62656
	ds_read_b64 v[162:163], v134 offset:34816
	s_waitcnt lgkmcnt(4)
	v_mfma_f32_16x16x32_bf16 v[150:153], v[150:153], v[42:45], 0
	s_waitcnt lgkmcnt(3)
	v_mfma_f32_16x16x32_bf16 v[150:153], v[154:157], v[46:49], v[150:153]
	s_waitcnt lgkmcnt(2)
	v_mfma_f32_16x16x32_bf16 v[150:153], v[158:161], v[50:53], v[150:153]
	s_waitcnt lgkmcnt(1)
	v_mfma_f32_16x16x32_bf16 v[150:153], v[246:249], v[56:59], v[150:153]
	v_sub_f32_e32 v242, v106, v242
	v_sub_f32_e32 v243, v106, v243
	v_sub_f32_e32 v244, v106, v244
	v_sub_f32_e32 v245, v106, v245
	v_mul_f32_e32 v242, 0x3fb8aa3b, v242
	v_mul_f32_e32 v243, 0x3fb8aa3b, v243
	v_mul_f32_e32 v244, 0x3fb8aa3b, v244
	v_mul_f32_e32 v245, 0x3fb8aa3b, v245
	v_exp_f32_e32 v242, v242
	v_exp_f32_e32 v243, v243
	v_exp_f32_e32 v244, v244
	v_exp_f32_e32 v245, v245
	v_mul_f32_e32 v226, v226, v242
	v_mul_f32_e32 v227, v227, v243
	v_mul_f32_e32 v228, v228, v244
	v_mul_f32_e32 v229, v229, v245
	v_cndmask_b32_e64 v226, v226, 0, s[16:17]
	v_cndmask_b32_e64 v227, 0, v227, s[18:19]
	v_cndmask_b32_e64 v228, v228, 0, s[20:21]
	v_cndmask_b32_e64 v229, v229, 0, s[22:23]
	v_mul_f32_e32 v106, 0x3fb8aa3b, v106
	v_exp_f32_e32 v106, v106
	v_cvt_pk_bf16_f32 v226, v226, v227
	v_cvt_pk_bf16_f32 v227, v228, v229
	v_cvt_pk_bf16_f32 v228, v206, v207
	v_cvt_pk_bf16_f32 v229, v208, v209
	v_cvt_pk_bf16_f32 v186, v186, v187
	v_cvt_pk_bf16_f32 v187, v188, v189
	v_mov_b32_e32 v188, 0
	v_mov_b32_e32 v189, 0
	v_mov_b32_e32 v168, s65
	ds_read_b128 v[170:173], v107 offset:62464
	ds_read_b128 v[174:177], v107 offset:62528
	ds_read_b128 v[178:181], v107 offset:62592
	ds_read_b128 v[182:185], v107 offset:62656
	ds_read_b64 v[166:167], v136 offset:34816
	ds_read_b32 v168, v168 offset:252
	v_lshl_add_u64 v[238:239], s[10:11], 0, v[98:99]
	v_mfma_f32_16x16x32_bf16 v[60:63], v[60:63], v[226:229], 0
	v_mfma_f32_16x16x32_bf16 v[60:63], v[64:67], v[186:189], v[60:63]
	v_mfma_f32_16x16x32_bf16 v[142:145], v[142:145], v[226:229], 0
	v_mfma_f32_16x16x32_bf16 v[142:145], v[146:149], v[186:189], v[142:145]
	s_waitcnt lgkmcnt(5)
; #define LAS __attribute__((address_space(3)))
; __device__ __forceinline__ unsigned pk2(float lo, float hi) { return f2bf(lo) | (f2bf(hi) << 16); }
; __device__ __forceinline__ void ssd_scan_mfma(const Ctx& c, bf16* X2, const float* DT, const float* a_log, const float* dskip, bool do_store) {
;     ...
;                     for (int k2 = 0; k2 < 2; ++k2) if (2 * k2 <= lt) { const LAS unsigned char* xp = xdb + k2 * 32 * 144 + pt * 32;
;                         Y = __builtin_amdgcn_mfma_f32_16x16x32_bf16(cat8(tr16(xp), tr16(xp + 16 * 144)), Lf[k2], Y, 0, 0, 0); }
; #pragma unroll
;                     for (int ks = 0; ks < 4; ++ks) { const bf16x8 sb = *(const LAS bf16x8*)(SBr + (16 * pt + l15) * 272 + (32 * ks + 8 * lg) * 2); Yo = __builtin_amdgcn_mfma_f32_16x16x32_bf16(sb, Cf[ks], Yo, 0, 0, 0); }
;                     const v2u xr = *(const LAS v2u*)(L + SS_XR + (16 * lt + l15) * 144 + (16 * pt + 4 * lg) * 2);
;                     const float y0 = Y[0] + el * Yo[0] + Dh * bflo(xr.x), y1 = Y[1] + el * Yo[1] + Dh * bfhi(xr.x), y2 = Y[2] + el * Yo[2] + Dh * bflo(xr.y), y3 = Y[3] + el * Yo[3] + Dh * bfhi(xr.y);
;                     v2u o; o.x = pk2(y0, y1); o.y = pk2(y2, y3);
;                     if (do_store) *(v2u*)(X2 + ((size_t)b * SEQ + t0 + 16 * lt + l15) * 6144 + h * 64 + 16 * pt + 4 * lg) = o; }
;                 const float e63 = __expf(CS[63]); const int pts = w >> 1;
;                 const LAS unsigned char* bb = L + SS_B + (8 * lg + tq) * 272 + tp * 8; const LAS unsigned char* xwb = L + SS_XW + (8 * lg + tq) * 144 + tp * 8 + pts * 32;
;                 bf16x8 Xf[2];
; #pragma unroll
;                 for (int ks = 0; ks < 2; ++ks) Xf[ks] = cat8(tr16(xwb + ks * 32 * 144), tr16(xwb + ks * 32 * 144 + 4 * 144));
; #pragma unroll
;                 for (int i = 0; i < 4; ++i) { const int nt = 4 * (w & 1) + i; ST[i] *= e63;
; #pragma unroll
;                     for (int ks = 0; ks < 2; ++ks) { const LAS unsigned char* bp = bb + ks * 32 * 272 + nt * 32;
;                         ST[i] = __builtin_amdgcn_mfma_f32_16x16x32_bf16(cat8(tr16(bp), tr16(bp + 4 * 272)), Xf[ks], ST[i], 0, 0, 0); }
;                     v2u q; q.x = pk2(ST[i][0], ST[i][1]); q.y = pk2(ST[i][2], ST[i][3]);
;                     *(LAS v2u*)(SBw + (16 * pts + l15) * 272 + (16 * nt + 4 * lg) * 2) = q; }
	v_mfma_f32_16x16x32_bf16 v[170:173], v[170:173], v[42:45], 0
	s_waitcnt lgkmcnt(4)
	v_mfma_f32_16x16x32_bf16 v[170:173], v[174:177], v[46:49], v[170:173]
	s_waitcnt lgkmcnt(3)
	v_mfma_f32_16x16x32_bf16 v[170:173], v[178:181], v[50:53], v[170:173]
	s_waitcnt lgkmcnt(2)
	v_mfma_f32_16x16x32_bf16 v[170:173], v[182:185], v[56:59], v[170:173]
	ds_read_b64_tr_b16 v[190:191], v137 offset:53248
	ds_read_b64_tr_b16 v[192:193], v137 offset:53824
	ds_read_b64_tr_b16 v[194:195], v137 offset:57856
	ds_read_b64_tr_b16 v[196:197], v137 offset:58432
	ds_read_b64_tr_b16 v[198:199], v54
	ds_read_b64_tr_b16 v[200:201], v54 offset:1088
	ds_read_b64_tr_b16 v[202:203], v54 offset:8704
	ds_read_b64_tr_b16 v[204:205], v54 offset:9792
	s_waitcnt lgkmcnt(8)
	v_mul_f32_e32 v168, 0x3fb8aa3b, v168
	v_exp_f32_e32 v168, v168
	v_fma_f32 v60, v106, v150, v60
	v_fma_f32 v61, v106, v151, v61
	v_fma_f32 v62, v106, v152, v62
	v_fma_f32 v63, v106, v153, v63
	v_lshlrev_b32_e32 v150, 16, v162
	v_and_b32_e32 v151, 0xffff0000, v162
	v_lshlrev_b32_e32 v152, 16, v163
	v_and_b32_e32 v153, 0xffff0000, v163
	v_fma_f32 v60, v94, v150, v60
	v_fma_f32 v61, v94, v151, v61
	v_fma_f32 v62, v95, v152, v62
	v_fma_f32 v63, v95, v153, v63
	v_cvt_pk_bf16_f32 v162, v60, v61
	v_cvt_pk_bf16_f32 v163, v62, v63
	global_store_dwordx2 v[238:239], v[162:163], off
	v_pk_mul_f32 v[18:19], v[18:19], v[168:169] op_sel_hi:[1,0]
	v_pk_mul_f32 v[20:21], v[20:21], v[168:169] op_sel_hi:[1,0]
	v_pk_mul_f32 v[14:15], v[14:15], v[168:169] op_sel_hi:[1,0]
	v_pk_mul_f32 v[16:17], v[16:17], v[168:169] op_sel_hi:[1,0]
	v_pk_mul_f32 v[10:11], v[10:11], v[168:169] op_sel_hi:[1,0]
	v_pk_mul_f32 v[12:13], v[12:13], v[168:169] op_sel_hi:[1,0]
	v_pk_mul_f32 v[6:7], v[6:7], v[168:169] op_sel_hi:[1,0]
	v_pk_mul_f32 v[8:9], v[8:9], v[168:169] op_sel_hi:[1,0]
	s_waitcnt lgkmcnt(2)
	v_mfma_f32_16x16x32_bf16 v[18:21], v[198:201], v[190:193], v[18:21]
	s_waitcnt lgkmcnt(0)
	v_mfma_f32_16x16x32_bf16 v[18:21], v[202:205], v[194:197], v[18:21]
	ds_read_b64_tr_b16 v[210:211], v54 offset:32
	ds_read_b64_tr_b16 v[212:213], v54 offset:1120
	ds_read_b64_tr_b16 v[214:215], v54 offset:8736
	ds_read_b64_tr_b16 v[216:217], v54 offset:9824
	v_fma_f32 v142, v106, v170, v142
	v_fma_f32 v143, v106, v171, v143
	v_fma_f32 v144, v106, v172, v144
	v_fma_f32 v145, v106, v173, v145
	v_lshlrev_b32_e32 v170, 16, v166
	v_and_b32_e32 v171, 0xffff0000, v166
	v_lshlrev_b32_e32 v172, 16, v167
	v_and_b32_e32 v173, 0xffff0000, v167
	v_fma_f32 v142, v94, v170, v142
	v_fma_f32 v143, v94, v171, v143
	v_fma_f32 v144, v95, v172, v144
	v_fma_f32 v145, v95, v173, v145
	v_cvt_pk_bf16_f32 v166, v142, v143
	v_cvt_pk_bf16_f32 v167, v144, v145
	global_store_dwordx2 v[238:239], v[166:167], off offset:32
	s_waitcnt lgkmcnt(2)
	v_mfma_f32_16x16x32_bf16 v[14:17], v[210:213], v[190:193], v[14:17]
	s_waitcnt lgkmcnt(0)
	v_mfma_f32_16x16x32_bf16 v[14:17], v[214:217], v[194:197], v[14:17]
	ds_read_b64_tr_b16 v[218:219], v54 offset:64
	ds_read_b64_tr_b16 v[220:221], v54 offset:1152
	ds_read_b64_tr_b16 v[222:223], v54 offset:8768
	ds_read_b64_tr_b16 v[224:225], v54 offset:9856
	v_cvt_pk_bf16_f32 v240, v18, v19
	v_cvt_pk_bf16_f32 v241, v20, v21
	ds_write_b64 v55, v[240:241] offset:62464
	s_waitcnt lgkmcnt(3)
	v_mfma_f32_16x16x32_bf16 v[10:13], v[218:221], v[190:193], v[10:13]
	s_waitcnt lgkmcnt(1)
	v_mfma_f32_16x16x32_bf16 v[10:13], v[222:225], v[194:197], v[10:13]
	ds_read_b64_tr_b16 v[230:231], v54 offset:96
	ds_read_b64_tr_b16 v[232:233], v54 offset:1184
	ds_read_b64_tr_b16 v[234:235], v54 offset:8800
	ds_read_b64_tr_b16 v[236:237], v54 offset:9888
	v_cvt_pk_bf16_f32 v242, v14, v15
	v_cvt_pk_bf16_f32 v243, v16, v17
	ds_write_b64 v55, v[242:243] offset:62496
	s_waitcnt lgkmcnt(3)
	v_mfma_f32_16x16x32_bf16 v[6:9], v[230:233], v[190:193], v[6:9]
	s_waitcnt lgkmcnt(1)
	v_mfma_f32_16x16x32_bf16 v[6:9], v[234:237], v[194:197], v[6:9]
	s_mov_b64 s[96:97], 0x4000
	s_add_i32 s63, s63, 1
	v_lshl_add_u64 v[96:97], v[96:97], 0, s[96:97]
	v_lshl_add_u64 v[98:99], v[98:99], 0, s[58:59]
	v_lshl_add_u64 v[100:101], v[100:101], 0, s[58:59]
	v_lshl_add_u64 v[102:103], v[102:103], 0, s[58:59]
	v_lshl_add_u64 v[104:105], v[104:105], 0, s[58:59]
	v_cvt_pk_bf16_f32 v240, v10, v11
	v_cvt_pk_bf16_f32 v241, v12, v13
	ds_write_b64 v55, v[240:241] offset:62528
	s_cmp_eq_u32 s63, 63
	v_cvt_pk_bf16_f32 v242, v6, v7
	v_cvt_pk_bf16_f32 v243, v8, v9
	ds_write_b64 v55, v[242:243] offset:62560
	s_setprio 0
	s_cbranch_scc1 .LBB0_483
	s_branch .LBB0_469
